# MLA residual epilogues: 7 of 8 second-batch old-hb loads hoisted next to first batch (one live VGPR parked in LDS spare)
# speedup vs baseline: 1.0038x; 1.0028x over previous
.LBB0_1056:
	v_lshl_or_b32 v166, s60, 8, v205
	v_lshl_add_u32 v170, s61, 8, v198
	v_ashrrev_i32_e32 v167, 31, v166
	v_lshlrev_b64 v[202:203], 1, v[166:167]
	v_ashrrev_i32_e32 v171, 31, v170
	v_lshl_add_u64 v[168:169], s[18:19], 0, v[202:203]
	v_lshlrev_b64 v[214:215], 11, v[170:171]
	v_lshl_add_u64 v[128:129], v[168:169], 0, v[214:215]
	global_load_dwordx4 v[210:213], v[128:129], off
	global_load_dwordx4 v[152:155], v[128:129], off offset:256
	v_or_b32_e32 v194, 16, v170
	v_ashrrev_i32_e32 v195, 31, v194
	v_or_b32_e32 v176, 32, v170
	v_lshlrev_b64 v[196:197], 11, v[194:195]
	v_ashrrev_i32_e32 v177, 31, v176
	v_or_b32_e32 v172, 48, v170
	v_lshl_add_u64 v[128:129], v[168:169], 0, v[196:197]
	v_lshlrev_b64 v[178:179], 11, v[176:177]
	v_ashrrev_i32_e32 v173, 31, v172
	global_load_dwordx4 v[148:151], v[128:129], off
	global_load_dwordx4 v[144:147], v[128:129], off offset:256
	v_lshl_add_u64 v[128:129], v[168:169], 0, v[178:179]
	v_lshlrev_b64 v[174:175], 11, v[172:173]
	global_load_dwordx4 v[140:143], v[128:129], off
	global_load_dwordx4 v[136:139], v[128:129], off offset:256
	v_lshl_add_u64 v[128:129], v[168:169], 0, v[174:175]
	global_load_dwordx4 v[132:135], v[128:129], off
	s_nop 0
	global_load_dwordx4 v[128:131], v[128:129], off offset:256
	v_lshlrev_b32_e32 v250, 2, v218
	v_add_u32_e32 v250, 0x20400, v250
	ds_write_b32 v250, v240
	v_add_u32_e32 v250, 0x80, v170
	v_ashrrev_i32_e32 v251, 31, v250
	v_lshlrev_b64 v[250:251], 11, v[250:251]
	v_lshl_add_u64 v[250:251], v[168:169], 0, v[250:251]
	global_load_dwordx4 v[222:225], v[250:251], off
	global_load_dwordx4 v[226:229], v[250:251], off offset:256
	v_add_u32_e32 v250, 0x90, v170
	v_ashrrev_i32_e32 v251, 31, v250
	v_lshlrev_b64 v[250:251], 11, v[250:251]
	v_lshl_add_u64 v[250:251], v[168:169], 0, v[250:251]
	global_load_dwordx4 v[230:233], v[250:251], off
	global_load_dwordx4 v[234:237], v[250:251], off offset:256
	v_add_u32_e32 v250, 0xa0, v170
	v_ashrrev_i32_e32 v251, 31, v250
	v_lshlrev_b64 v[250:251], 11, v[250:251]
	v_lshl_add_u64 v[250:251], v[168:169], 0, v[250:251]
	global_load_dwordx4 v[238:241], v[250:251], off
	global_load_dwordx4 v[242:245], v[250:251], off offset:256
	v_add_u32_e32 v250, 0xb0, v170
	v_ashrrev_i32_e32 v251, 31, v250
	v_lshlrev_b64 v[250:251], 11, v[250:251]
	v_lshl_add_u64 v[250:251], v[168:169], 0, v[250:251]
	global_load_dwordx4 v[246:249], v[250:251], off
	v_and_b32_e32 v208, 64, v219
	v_xor_b32_e32 v207, 16, v219
	v_add_u32_e32 v208, 64, v208
	v_cmp_lt_i32_e32 vcc, v207, v208
	v_xor_b32_e32 v209, 32, v219
	s_lshl_b32 s28, s60, 2
	v_cndmask_b32_e32 v207, v219, v207, vcc
	v_cmp_lt_i32_e32 vcc, v209, v208
	v_lshlrev_b32_e32 v207, 2, v207
	s_ashr_i32 s29, s28, 31
	v_cndmask_b32_e32 v208, v219, v209, vcc
	v_lshlrev_b32_e32 v208, 2, v208
	s_waitcnt vmcnt(0)
	v_lshlrev_b32_e32 v216, 16, v210
	v_and_b32_e32 v217, 0xffff0000, v210
	v_lshlrev_b32_e32 v210, 16, v211
	v_and_b32_e32 v211, 0xffff0000, v211
	v_lshlrev_b32_e32 v220, 16, v212
	v_and_b32_e32 v221, 0xffff0000, v212
	v_lshlrev_b32_e32 v212, 16, v213
	v_and_b32_e32 v213, 0xffff0000, v213
	v_pk_add_f32 v[210:211], v[122:123], v[210:211]
	v_pk_add_f32 v[216:217], v[120:121], v[216:217]
	v_pk_add_f32 v[126:127], v[126:127], v[212:213]
	v_pk_add_f32 v[124:125], v[124:125], v[220:221]
	v_lshl_add_u64 v[212:213], s[18:19], 0, v[214:215]
	v_cvt_pk_bf16_f32 v120, v216, v217
	v_cvt_pk_bf16_f32 v121, v210, v211
	v_cvt_pk_bf16_f32 v122, v124, v125
	v_cvt_pk_bf16_f32 v123, v126, v127
	v_lshl_add_u64 v[202:203], v[212:213], 0, v[202:203]
	global_store_dwordx4 v[202:203], v[120:123], off
	s_nop 1
	v_mul_f32_e32 v120, v217, v217
	v_mul_f32_e32 v121, v211, v211
	v_fmac_f32_e32 v120, v216, v216
	v_fmac_f32_e32 v121, v210, v210
	v_add_f32_e32 v120, v120, v121
	v_mul_f32_e32 v121, v125, v125
	v_mul_f32_e32 v122, v127, v127
	v_fmac_f32_e32 v121, v124, v124
	v_fmac_f32_e32 v122, v126, v126
	v_add_f32_e32 v121, v121, v122
	v_add_f32_e32 v209, v120, v121
	v_lshlrev_b32_e32 v120, 16, v152
	v_and_b32_e32 v121, 0xffff0000, v152
	v_lshlrev_b32_e32 v122, 16, v153
	v_and_b32_e32 v123, 0xffff0000, v153
	v_lshlrev_b32_e32 v124, 16, v154
	v_and_b32_e32 v125, 0xffff0000, v154
	v_lshlrev_b32_e32 v126, 16, v155
	v_and_b32_e32 v127, 0xffff0000, v155
	v_pk_add_f32 v[118:119], v[118:119], v[122:123]
	v_pk_add_f32 v[116:117], v[116:117], v[120:121]
	v_pk_add_f32 v[120:121], v[114:115], v[126:127]
	v_pk_add_f32 v[122:123], v[112:113], v[124:125]
	v_cvt_pk_bf16_f32 v112, v116, v117
	v_cvt_pk_bf16_f32 v113, v118, v119
	v_cvt_pk_bf16_f32 v114, v122, v123
	v_cvt_pk_bf16_f32 v115, v120, v121
	global_store_dwordx4 v[202:203], v[112:115], off offset:256
	s_nop 1
	v_mul_f32_e32 v112, v117, v117
	v_mul_f32_e32 v113, v119, v119
	v_fmac_f32_e32 v112, v116, v116
	v_fmac_f32_e32 v113, v118, v118
	v_add_f32_e32 v112, v112, v113
	v_mul_f32_e32 v113, v123, v123
	v_mul_f32_e32 v114, v121, v121
	v_fmac_f32_e32 v113, v122, v122
	v_fmac_f32_e32 v114, v120, v120
	v_add_f32_e32 v113, v113, v114
	v_add_f32_e32 v112, v112, v113
	v_add_f32_e32 v112, v209, v112
	ds_bpermute_b32 v113, v207, v112
	s_waitcnt lgkmcnt(0)
	v_add_f32_e32 v112, v112, v113
	ds_bpermute_b32 v113, v208, v112
	s_and_saveexec_b64 s[10:11], s[40:41]
	s_cbranch_execz .LBB0_1058
	s_waitcnt lgkmcnt(0)
	v_add_f32_e32 v114, v112, v113
	v_lshlrev_b64 v[112:113], 6, v[170:171]
	v_lshl_add_u64 v[112:113], s[0:1], 0, v[112:113]
	v_lshl_add_u64 v[112:113], s[28:29], 2, v[112:113]
	s_lshl_b32 s64, s47, 2
	v_lshl_add_u64 v[112:113], v[112:113], 0, s[64:65]
	global_store_dword v[112:113], v114, off

.LBB0_1064:
	s_or_b64 exec, exec, s[10:11]
	v_add_u32_e32 v104, 0x80, v170
	v_ashrrev_i32_e32 v105, 31, v104
	v_lshlrev_b64 v[110:111], 11, v[104:105]
	s_waitcnt lgkmcnt(0)
	v_lshl_add_u64 v[64:65], v[168:169], 0, v[110:111]
	v_add_u32_e32 v100, 0x90, v170
	v_ashrrev_i32_e32 v101, 31, v100
	v_add_u32_e32 v96, 0xa0, v170
	v_lshlrev_b64 v[102:103], 11, v[100:101]
	v_ashrrev_i32_e32 v97, 31, v96
	v_add_u32_e32 v92, 0xb0, v170
	v_lshl_add_u64 v[64:65], v[168:169], 0, v[102:103]
	v_lshlrev_b64 v[98:99], 11, v[96:97]
	v_ashrrev_i32_e32 v93, 31, v92
	v_lshl_add_u64 v[64:65], v[168:169], 0, v[98:99]
	v_lshlrev_b64 v[94:95], 11, v[92:93]
	v_lshl_add_u64 v[64:65], v[168:169], 0, v[94:95]
	s_nop 0
	global_load_dwordx4 v[64:67], v[64:65], off offset:256
	v_lshl_add_u64 v[110:111], s[18:19], 0, v[110:111]
	v_lshl_add_u64 v[110:111], v[166:167], 1, v[110:111]
	v_lshlrev_b32_e32 v112, 16, v222
	v_and_b32_e32 v113, 0xffff0000, v222
	v_lshlrev_b32_e32 v106, 16, v223
	v_and_b32_e32 v107, 0xffff0000, v223
	v_lshlrev_b32_e32 v114, 16, v224
	v_and_b32_e32 v115, 0xffff0000, v224
	v_lshlrev_b32_e32 v108, 16, v225
	v_and_b32_e32 v109, 0xffff0000, v225
	v_pk_add_f32 v[62:63], v[62:63], v[106:107]
	v_pk_add_f32 v[60:61], v[60:61], v[112:113]
	v_pk_add_f32 v[106:107], v[58:59], v[108:109]
	v_pk_add_f32 v[108:109], v[56:57], v[114:115]
	v_cvt_pk_bf16_f32 v56, v60, v61
	v_cvt_pk_bf16_f32 v57, v62, v63
	v_cvt_pk_bf16_f32 v58, v108, v109
	v_cvt_pk_bf16_f32 v59, v106, v107
	global_store_dwordx4 v[110:111], v[56:59], off
	s_nop 1
	v_mul_f32_e32 v56, v61, v61
	v_mul_f32_e32 v57, v63, v63
	v_fmac_f32_e32 v56, v60, v60
	v_fmac_f32_e32 v57, v62, v62
	v_add_f32_e32 v56, v56, v57
	v_mul_f32_e32 v57, v109, v109
	v_mul_f32_e32 v58, v107, v107
	v_fmac_f32_e32 v57, v108, v108
	v_fmac_f32_e32 v58, v106, v106
	v_add_f32_e32 v57, v57, v58
	v_add_f32_e32 v106, v56, v57
	v_lshlrev_b32_e32 v56, 16, v226
	v_and_b32_e32 v57, 0xffff0000, v226
	v_lshlrev_b32_e32 v58, 16, v227
	v_and_b32_e32 v59, 0xffff0000, v227
	v_lshlrev_b32_e32 v60, 16, v228
	v_and_b32_e32 v61, 0xffff0000, v228
	v_lshlrev_b32_e32 v62, 16, v229
	v_and_b32_e32 v63, 0xffff0000, v229
	v_pk_add_f32 v[54:55], v[54:55], v[58:59]
	v_pk_add_f32 v[52:53], v[52:53], v[56:57]
	v_pk_add_f32 v[56:57], v[50:51], v[62:63]
	v_pk_add_f32 v[58:59], v[48:49], v[60:61]
	v_cvt_pk_bf16_f32 v48, v52, v53
	v_cvt_pk_bf16_f32 v49, v54, v55
	v_cvt_pk_bf16_f32 v50, v58, v59
	v_cvt_pk_bf16_f32 v51, v56, v57
	global_store_dwordx4 v[110:111], v[48:51], off offset:256
	s_nop 1
	v_mul_f32_e32 v48, v53, v53
	v_mul_f32_e32 v49, v55, v55
	v_fmac_f32_e32 v48, v52, v52
	v_fmac_f32_e32 v49, v54, v54
	v_add_f32_e32 v48, v48, v49
	v_mul_f32_e32 v49, v59, v59
	v_mul_f32_e32 v50, v57, v57
	v_fmac_f32_e32 v49, v58, v58
	v_fmac_f32_e32 v50, v56, v56
	v_add_f32_e32 v49, v49, v50
	v_add_f32_e32 v48, v48, v49
	v_add_f32_e32 v48, v106, v48
	ds_bpermute_b32 v49, v207, v48
	s_waitcnt lgkmcnt(0)
	v_add_f32_e32 v48, v48, v49
	ds_bpermute_b32 v49, v208, v48
	s_and_saveexec_b64 s[10:11], s[40:41]
	s_cbranch_execz .LBB0_1066
	s_waitcnt lgkmcnt(0)
	v_add_f32_e32 v50, v48, v49
	v_lshlrev_b64 v[48:49], 6, v[104:105]
	v_lshl_add_u64 v[48:49], s[0:1], 0, v[48:49]
	v_lshl_add_u64 v[48:49], s[28:29], 2, v[48:49]
	s_lshl_b32 s64, s47, 2
	v_lshl_add_u64 v[48:49], v[48:49], 0, s[64:65]
	global_store_dword v[48:49], v50, off
.LBB0_1066:
	s_or_b64 exec, exec, s[10:11]
	v_lshlrev_b32_e32 v48, 16, v230
	s_waitcnt lgkmcnt(0)
	v_and_b32_e32 v49, 0xffff0000, v230
	v_lshlrev_b32_e32 v50, 16, v231
	v_and_b32_e32 v51, 0xffff0000, v231
	v_lshlrev_b32_e32 v52, 16, v232
	v_and_b32_e32 v53, 0xffff0000, v232
	v_pk_add_f32 v[44:45], v[44:45], v[48:49]
	v_pk_add_f32 v[46:47], v[46:47], v[50:51]
	v_pk_add_f32 v[50:51], v[40:41], v[52:53]
	v_cvt_pk_bf16_f32 v40, v44, v45
	v_mul_f32_e32 v45, v45, v45
	v_lshlrev_b32_e32 v54, 16, v233
	v_and_b32_e32 v55, 0xffff0000, v233
	v_fmac_f32_e32 v45, v44, v44
	v_mul_f32_e32 v44, v47, v47
	v_pk_add_f32 v[48:49], v[42:43], v[54:55]
	v_fmac_f32_e32 v44, v46, v46
	v_cvt_pk_bf16_f32 v41, v46, v47
	v_add_f32_e32 v44, v45, v44
	v_mul_f32_e32 v45, v51, v51
	v_mul_f32_e32 v46, v49, v49
	v_fmac_f32_e32 v45, v50, v50
	v_fmac_f32_e32 v46, v48, v48
	v_add_f32_e32 v45, v45, v46
	v_add_f32_e32 v52, v44, v45
	v_lshlrev_b32_e32 v44, 16, v234
	v_and_b32_e32 v45, 0xffff0000, v234
	v_lshlrev_b32_e32 v46, 16, v235
	v_and_b32_e32 v47, 0xffff0000, v235
	v_cvt_pk_bf16_f32 v43, v48, v49
	v_lshlrev_b32_e32 v48, 16, v236
	v_and_b32_e32 v49, 0xffff0000, v236
	v_pk_add_f32 v[38:39], v[38:39], v[46:47]
	v_pk_add_f32 v[36:37], v[36:37], v[44:45]
	v_cvt_pk_bf16_f32 v42, v50, v51
	v_lshlrev_b32_e32 v50, 16, v237
	v_and_b32_e32 v51, 0xffff0000, v237
	v_pk_add_f32 v[46:47], v[32:33], v[48:49]
	v_mul_f32_e32 v32, v37, v37
	v_mul_f32_e32 v33, v39, v39
	v_pk_add_f32 v[44:45], v[34:35], v[50:51]
	v_fmac_f32_e32 v32, v36, v36
	v_fmac_f32_e32 v33, v38, v38
	v_add_f32_e32 v32, v32, v33
	v_mul_f32_e32 v33, v47, v47
	v_mul_f32_e32 v34, v45, v45
	v_fmac_f32_e32 v33, v46, v46
	v_fmac_f32_e32 v34, v44, v44
	v_add_f32_e32 v33, v33, v34
	v_add_f32_e32 v32, v32, v33
	v_add_f32_e32 v35, v52, v32
	ds_bpermute_b32 v50, v207, v35
	v_lshl_add_u64 v[32:33], s[18:19], 0, v[102:103]
	v_lshl_add_u64 v[48:49], v[166:167], 1, v[32:33]
	v_cvt_pk_bf16_f32 v34, v36, v37
	v_cvt_pk_bf16_f32 v36, v46, v47
	s_waitcnt lgkmcnt(0)
	v_add_f32_e32 v32, v35, v50
	ds_bpermute_b32 v33, v208, v32
	v_cvt_pk_bf16_f32 v35, v38, v39
	v_cvt_pk_bf16_f32 v37, v44, v45
	global_store_dwordx4 v[48:49], v[40:43], off
	global_store_dwordx4 v[48:49], v[34:37], off offset:256
	s_and_saveexec_b64 s[10:11], s[40:41]
	s_cbranch_execz .LBB0_1068
	s_waitcnt lgkmcnt(0)
	v_add_f32_e32 v34, v32, v33
	v_lshlrev_b64 v[32:33], 6, v[100:101]
	v_lshl_add_u64 v[32:33], s[0:1], 0, v[32:33]
	v_lshl_add_u64 v[32:33], s[28:29], 2, v[32:33]
	s_lshl_b32 s64, s47, 2
	v_lshl_add_u64 v[32:33], v[32:33], 0, s[64:65]
	global_store_dword v[32:33], v34, off
.LBB0_1068:
	s_or_b64 exec, exec, s[10:11]
	v_lshlrev_b32_e32 v32, 16, v238
	s_waitcnt lgkmcnt(0)
	v_and_b32_e32 v33, 0xffff0000, v238
	v_lshlrev_b32_e32 v34, 16, v239
	v_and_b32_e32 v35, 0xffff0000, v239
	v_lshlrev_b32_e32 v36, 16, v240
	v_and_b32_e32 v37, 0xffff0000, v240
	v_pk_add_f32 v[28:29], v[28:29], v[32:33]
	v_pk_add_f32 v[30:31], v[30:31], v[34:35]
	v_pk_add_f32 v[34:35], v[24:25], v[36:37]
	v_cvt_pk_bf16_f32 v24, v28, v29
	v_mul_f32_e32 v29, v29, v29
	v_lshlrev_b32_e32 v38, 16, v241
	v_and_b32_e32 v39, 0xffff0000, v241
	v_fmac_f32_e32 v29, v28, v28
	v_mul_f32_e32 v28, v31, v31
	v_pk_add_f32 v[32:33], v[26:27], v[38:39]
	v_fmac_f32_e32 v28, v30, v30
	v_cvt_pk_bf16_f32 v25, v30, v31
	v_add_f32_e32 v28, v29, v28
	v_mul_f32_e32 v29, v35, v35
	v_mul_f32_e32 v30, v33, v33
	v_fmac_f32_e32 v29, v34, v34
	v_fmac_f32_e32 v30, v32, v32
	v_add_f32_e32 v29, v29, v30
	v_add_f32_e32 v36, v28, v29
	v_lshlrev_b32_e32 v28, 16, v242
	v_and_b32_e32 v29, 0xffff0000, v242
	v_lshlrev_b32_e32 v30, 16, v243
	v_and_b32_e32 v31, 0xffff0000, v243
	v_cvt_pk_bf16_f32 v27, v32, v33
	v_lshlrev_b32_e32 v32, 16, v244
	v_and_b32_e32 v33, 0xffff0000, v244
	v_pk_add_f32 v[22:23], v[22:23], v[30:31]
	v_pk_add_f32 v[20:21], v[20:21], v[28:29]
	v_cvt_pk_bf16_f32 v26, v34, v35
	v_lshlrev_b32_e32 v34, 16, v245
	v_and_b32_e32 v35, 0xffff0000, v245
	v_pk_add_f32 v[30:31], v[16:17], v[32:33]
	v_mul_f32_e32 v16, v21, v21
	v_mul_f32_e32 v17, v23, v23
	v_pk_add_f32 v[28:29], v[18:19], v[34:35]
	v_fmac_f32_e32 v16, v20, v20
	v_fmac_f32_e32 v17, v22, v22
	v_add_f32_e32 v16, v16, v17
	v_mul_f32_e32 v17, v31, v31
	v_mul_f32_e32 v18, v29, v29
	v_fmac_f32_e32 v17, v30, v30
	v_fmac_f32_e32 v18, v28, v28
	v_add_f32_e32 v17, v17, v18
	v_add_f32_e32 v16, v16, v17
	v_add_f32_e32 v19, v36, v16
	ds_bpermute_b32 v34, v207, v19
	v_lshl_add_u64 v[16:17], s[18:19], 0, v[98:99]
	v_lshl_add_u64 v[32:33], v[166:167], 1, v[16:17]
	v_cvt_pk_bf16_f32 v18, v20, v21
	v_cvt_pk_bf16_f32 v20, v30, v31
	s_waitcnt lgkmcnt(0)
	v_add_f32_e32 v16, v19, v34
	ds_bpermute_b32 v17, v208, v16
	v_cvt_pk_bf16_f32 v19, v22, v23
	v_cvt_pk_bf16_f32 v21, v28, v29
	global_store_dwordx4 v[32:33], v[24:27], off
	global_store_dwordx4 v[32:33], v[18:21], off offset:256
	s_and_saveexec_b64 s[10:11], s[40:41]
	s_cbranch_execz .LBB0_1070
	s_waitcnt lgkmcnt(0)
	v_add_f32_e32 v18, v16, v17
	v_lshlrev_b64 v[16:17], 6, v[96:97]
	v_lshl_add_u64 v[16:17], s[0:1], 0, v[16:17]
	v_lshl_add_u64 v[16:17], s[28:29], 2, v[16:17]
	s_lshl_b32 s64, s47, 2
	v_lshl_add_u64 v[16:17], v[16:17], 0, s[64:65]
	global_store_dword v[16:17], v18, off
.LBB0_1070:
	s_or_b64 exec, exec, s[10:11]
	v_lshlrev_b32_e32 v16, 16, v246
	s_waitcnt lgkmcnt(0)
	v_and_b32_e32 v17, 0xffff0000, v246
	v_lshlrev_b32_e32 v18, 16, v247
	v_and_b32_e32 v19, 0xffff0000, v247
	v_lshlrev_b32_e32 v20, 16, v248
	v_and_b32_e32 v21, 0xffff0000, v248
	v_pk_add_f32 v[12:13], v[12:13], v[16:17]
	v_pk_add_f32 v[14:15], v[14:15], v[18:19]
	v_pk_add_f32 v[18:19], v[8:9], v[20:21]
	v_cvt_pk_bf16_f32 v8, v12, v13
	v_mul_f32_e32 v13, v13, v13
	v_lshlrev_b32_e32 v22, 16, v249
	v_and_b32_e32 v23, 0xffff0000, v249
	v_fmac_f32_e32 v13, v12, v12
	v_mul_f32_e32 v12, v15, v15
	v_pk_add_f32 v[16:17], v[10:11], v[22:23]
	v_fmac_f32_e32 v12, v14, v14
	v_cvt_pk_bf16_f32 v9, v14, v15
	v_add_f32_e32 v12, v13, v12
	v_mul_f32_e32 v13, v19, v19
	v_mul_f32_e32 v14, v17, v17
	v_fmac_f32_e32 v13, v18, v18
	v_fmac_f32_e32 v14, v16, v16
	v_add_f32_e32 v13, v13, v14
	v_add_f32_e32 v20, v12, v13
	s_waitcnt vmcnt(8)
	v_lshlrev_b32_e32 v12, 16, v64
	v_and_b32_e32 v13, 0xffff0000, v64
	v_lshlrev_b32_e32 v14, 16, v65
	v_and_b32_e32 v15, 0xffff0000, v65
	v_cvt_pk_bf16_f32 v11, v16, v17
	v_lshlrev_b32_e32 v16, 16, v66
	v_and_b32_e32 v17, 0xffff0000, v66
	v_pk_add_f32 v[6:7], v[6:7], v[14:15]
	v_pk_add_f32 v[4:5], v[4:5], v[12:13]
	v_cvt_pk_bf16_f32 v10, v18, v19
	v_lshlrev_b32_e32 v18, 16, v67
	v_and_b32_e32 v19, 0xffff0000, v67
	v_pk_add_f32 v[14:15], v[0:1], v[16:17]
	v_mul_f32_e32 v0, v5, v5
	v_mul_f32_e32 v1, v7, v7
	v_pk_add_f32 v[12:13], v[2:3], v[18:19]
	v_fmac_f32_e32 v0, v4, v4
	v_fmac_f32_e32 v1, v6, v6
	v_add_f32_e32 v0, v0, v1
	v_mul_f32_e32 v1, v15, v15
	v_mul_f32_e32 v2, v13, v13
	v_fmac_f32_e32 v1, v14, v14
	v_fmac_f32_e32 v2, v12, v12
	v_add_f32_e32 v1, v1, v2
	v_add_f32_e32 v0, v0, v1
	v_add_f32_e32 v3, v20, v0
	ds_bpermute_b32 v18, v207, v3
	v_lshl_add_u64 v[0:1], s[18:19], 0, v[94:95]
	v_lshl_add_u64 v[16:17], v[166:167], 1, v[0:1]
	v_cvt_pk_bf16_f32 v2, v4, v5
	v_cvt_pk_bf16_f32 v4, v14, v15
	s_waitcnt lgkmcnt(0)
	v_add_f32_e32 v0, v3, v18
	ds_bpermute_b32 v1, v208, v0
	v_cvt_pk_bf16_f32 v3, v6, v7
	v_cvt_pk_bf16_f32 v5, v12, v13
	global_store_dwordx4 v[16:17], v[8:11], off
	global_store_dwordx4 v[16:17], v[2:5], off offset:256
	s_and_saveexec_b64 s[10:11], s[40:41]
	s_cbranch_execz .LBB0_1072
	s_waitcnt lgkmcnt(0)
	v_add_f32_e32 v2, v0, v1
	v_lshlrev_b64 v[0:1], 6, v[92:93]
	v_lshl_add_u64 v[0:1], s[0:1], 0, v[0:1]
	v_lshl_add_u64 v[0:1], s[28:29], 2, v[0:1]
	s_lshl_b32 s64, s47, 2
	v_lshl_add_u64 v[0:1], v[0:1], 0, s[64:65]
	global_store_dword v[0:1], v2, off
.LBB0_1072:
	s_or_b64 exec, exec, s[10:11]
	v_lshlrev_b32_e32 v250, 2, v218
	v_add_u32_e32 v250, 0x20400, v250
	ds_read_b32 v240, v250
	s_waitcnt lgkmcnt(0)
	s_and_b64 vcc, exec, s[42:43]
	s_mov_b64 s[10:11], -1
	s_cbranch_vccnz .LBB0_1040
	s_andn2_b64 vcc, exec, s[14:15]
	s_cbranch_vccnz .LBB0_1039
	s_barrier
	s_branch .LBB0_1039

.LBB0_1228:
	v_lshl_or_b32 v166, s58, 8, v205
	v_lshl_add_u32 v170, s59, 8, v198
	v_ashrrev_i32_e32 v167, 31, v166
	v_lshlrev_b64 v[202:203], 1, v[166:167]
	v_ashrrev_i32_e32 v171, 31, v170
	v_lshl_add_u64 v[168:169], s[16:17], 0, v[202:203]
	v_lshlrev_b64 v[214:215], 11, v[170:171]
	v_lshl_add_u64 v[128:129], v[168:169], 0, v[214:215]
	global_load_dwordx4 v[210:213], v[128:129], off
	global_load_dwordx4 v[152:155], v[128:129], off offset:256
	v_or_b32_e32 v194, 16, v170
	v_ashrrev_i32_e32 v195, 31, v194
	v_or_b32_e32 v176, 32, v170
	v_lshlrev_b64 v[196:197], 11, v[194:195]
	v_ashrrev_i32_e32 v177, 31, v176
	v_or_b32_e32 v172, 48, v170
	v_lshl_add_u64 v[128:129], v[168:169], 0, v[196:197]
	v_lshlrev_b64 v[178:179], 11, v[176:177]
	v_ashrrev_i32_e32 v173, 31, v172
	global_load_dwordx4 v[148:151], v[128:129], off
	global_load_dwordx4 v[144:147], v[128:129], off offset:256
	v_lshl_add_u64 v[128:129], v[168:169], 0, v[178:179]
	v_lshlrev_b64 v[174:175], 11, v[172:173]
	global_load_dwordx4 v[140:143], v[128:129], off
	global_load_dwordx4 v[136:139], v[128:129], off offset:256
	v_lshl_add_u64 v[128:129], v[168:169], 0, v[174:175]
	global_load_dwordx4 v[132:135], v[128:129], off
	s_nop 0
	global_load_dwordx4 v[128:131], v[128:129], off offset:256
	v_lshlrev_b32_e32 v250, 2, v218
	v_add_u32_e32 v250, 0x20400, v250
	ds_write_b32 v250, v240
	v_add_u32_e32 v250, 0x80, v170
	v_ashrrev_i32_e32 v251, 31, v250
	v_lshlrev_b64 v[250:251], 11, v[250:251]
	v_lshl_add_u64 v[250:251], v[168:169], 0, v[250:251]
	global_load_dwordx4 v[222:225], v[250:251], off
	global_load_dwordx4 v[226:229], v[250:251], off offset:256
	v_add_u32_e32 v250, 0x90, v170
	v_ashrrev_i32_e32 v251, 31, v250
	v_lshlrev_b64 v[250:251], 11, v[250:251]
	v_lshl_add_u64 v[250:251], v[168:169], 0, v[250:251]
	global_load_dwordx4 v[230:233], v[250:251], off
	global_load_dwordx4 v[234:237], v[250:251], off offset:256
	v_add_u32_e32 v250, 0xa0, v170
	v_ashrrev_i32_e32 v251, 31, v250
	v_lshlrev_b64 v[250:251], 11, v[250:251]
	v_lshl_add_u64 v[250:251], v[168:169], 0, v[250:251]
	global_load_dwordx4 v[238:241], v[250:251], off
	global_load_dwordx4 v[242:245], v[250:251], off offset:256
	v_add_u32_e32 v250, 0xb0, v170
	v_ashrrev_i32_e32 v251, 31, v250
	v_lshlrev_b64 v[250:251], 11, v[250:251]
	v_lshl_add_u64 v[250:251], v[168:169], 0, v[250:251]
	global_load_dwordx4 v[246:249], v[250:251], off
	v_and_b32_e32 v208, 64, v219
	v_xor_b32_e32 v207, 16, v219
	v_add_u32_e32 v208, 64, v208
	v_cmp_lt_i32_e32 vcc, v207, v208
	v_xor_b32_e32 v209, 32, v219
	s_lshl_b32 s26, s58, 2
	v_cndmask_b32_e32 v207, v219, v207, vcc
	v_cmp_lt_i32_e32 vcc, v209, v208
	v_lshlrev_b32_e32 v207, 2, v207
	s_ashr_i32 s27, s26, 31
	v_cndmask_b32_e32 v208, v219, v209, vcc
	v_lshlrev_b32_e32 v208, 2, v208
	s_waitcnt vmcnt(0)
	v_lshlrev_b32_e32 v216, 16, v210
	v_and_b32_e32 v217, 0xffff0000, v210
	v_lshlrev_b32_e32 v210, 16, v211
	v_and_b32_e32 v211, 0xffff0000, v211
	v_lshlrev_b32_e32 v220, 16, v212
	v_and_b32_e32 v221, 0xffff0000, v212
	v_lshlrev_b32_e32 v212, 16, v213
	v_and_b32_e32 v213, 0xffff0000, v213
	v_pk_add_f32 v[210:211], v[122:123], v[210:211]
	v_pk_add_f32 v[216:217], v[120:121], v[216:217]
	v_pk_add_f32 v[126:127], v[126:127], v[212:213]
	v_pk_add_f32 v[124:125], v[124:125], v[220:221]
	v_lshl_add_u64 v[212:213], s[16:17], 0, v[214:215]
	v_cvt_pk_bf16_f32 v120, v216, v217
	v_cvt_pk_bf16_f32 v121, v210, v211
	v_cvt_pk_bf16_f32 v122, v124, v125
	v_cvt_pk_bf16_f32 v123, v126, v127
	v_lshl_add_u64 v[202:203], v[212:213], 0, v[202:203]
	global_store_dwordx4 v[202:203], v[120:123], off
	s_nop 1
	v_mul_f32_e32 v120, v217, v217
	v_mul_f32_e32 v121, v211, v211
	v_fmac_f32_e32 v120, v216, v216
	v_fmac_f32_e32 v121, v210, v210
	v_add_f32_e32 v120, v120, v121
	v_mul_f32_e32 v121, v125, v125
	v_mul_f32_e32 v122, v127, v127
	v_fmac_f32_e32 v121, v124, v124
	v_fmac_f32_e32 v122, v126, v126
	v_add_f32_e32 v121, v121, v122
	v_add_f32_e32 v209, v120, v121
	v_lshlrev_b32_e32 v120, 16, v152
	v_and_b32_e32 v121, 0xffff0000, v152
	v_lshlrev_b32_e32 v122, 16, v153
	v_and_b32_e32 v123, 0xffff0000, v153
	v_lshlrev_b32_e32 v124, 16, v154
	v_and_b32_e32 v125, 0xffff0000, v154
	v_lshlrev_b32_e32 v126, 16, v155
	v_and_b32_e32 v127, 0xffff0000, v155
	v_pk_add_f32 v[118:119], v[118:119], v[122:123]
	v_pk_add_f32 v[116:117], v[116:117], v[120:121]
	v_pk_add_f32 v[120:121], v[114:115], v[126:127]
	v_pk_add_f32 v[122:123], v[112:113], v[124:125]
	v_cvt_pk_bf16_f32 v112, v116, v117
	v_cvt_pk_bf16_f32 v113, v118, v119
	v_cvt_pk_bf16_f32 v114, v122, v123
	v_cvt_pk_bf16_f32 v115, v120, v121
	global_store_dwordx4 v[202:203], v[112:115], off offset:256
	s_nop 1
	v_mul_f32_e32 v112, v117, v117
	v_mul_f32_e32 v113, v119, v119
	v_fmac_f32_e32 v112, v116, v116
	v_fmac_f32_e32 v113, v118, v118
	v_add_f32_e32 v112, v112, v113
	v_mul_f32_e32 v113, v123, v123
	v_mul_f32_e32 v114, v121, v121
	v_fmac_f32_e32 v113, v122, v122
	v_fmac_f32_e32 v114, v120, v120
	v_add_f32_e32 v113, v113, v114
	v_add_f32_e32 v112, v112, v113
	v_add_f32_e32 v112, v209, v112
	ds_bpermute_b32 v113, v207, v112
	s_waitcnt lgkmcnt(0)
	v_add_f32_e32 v112, v112, v113
	ds_bpermute_b32 v113, v208, v112
	s_and_saveexec_b64 s[10:11], s[40:41]
	s_cbranch_execz .LBB0_1230
	s_waitcnt lgkmcnt(0)
	v_add_f32_e32 v114, v112, v113
	v_lshlrev_b64 v[112:113], 6, v[170:171]
	v_lshl_add_u64 v[112:113], s[0:1], 0, v[112:113]
	v_lshl_add_u64 v[112:113], s[26:27], 2, v[112:113]
	s_lshl_b32 s64, s39, 2
	v_lshl_add_u64 v[112:113], v[112:113], 0, s[64:65]
	global_store_dword v[112:113], v114, off

.LBB0_1236:
	s_or_b64 exec, exec, s[10:11]
	v_add_u32_e32 v104, 0x80, v170
	v_ashrrev_i32_e32 v105, 31, v104
	v_lshlrev_b64 v[110:111], 11, v[104:105]
	s_waitcnt lgkmcnt(0)
	v_lshl_add_u64 v[64:65], v[168:169], 0, v[110:111]
	v_add_u32_e32 v100, 0x90, v170
	v_ashrrev_i32_e32 v101, 31, v100
	v_add_u32_e32 v96, 0xa0, v170
	v_lshlrev_b64 v[102:103], 11, v[100:101]
	v_ashrrev_i32_e32 v97, 31, v96
	v_add_u32_e32 v92, 0xb0, v170
	v_lshl_add_u64 v[64:65], v[168:169], 0, v[102:103]
	v_lshlrev_b64 v[98:99], 11, v[96:97]
	v_ashrrev_i32_e32 v93, 31, v92
	v_lshl_add_u64 v[64:65], v[168:169], 0, v[98:99]
	v_lshlrev_b64 v[94:95], 11, v[92:93]
	v_lshl_add_u64 v[64:65], v[168:169], 0, v[94:95]
	s_nop 0
	global_load_dwordx4 v[64:67], v[64:65], off offset:256
	v_lshl_add_u64 v[110:111], s[16:17], 0, v[110:111]
	v_lshl_add_u64 v[110:111], v[166:167], 1, v[110:111]
	v_lshlrev_b32_e32 v112, 16, v222
	v_and_b32_e32 v113, 0xffff0000, v222
	v_lshlrev_b32_e32 v106, 16, v223
	v_and_b32_e32 v107, 0xffff0000, v223
	v_lshlrev_b32_e32 v114, 16, v224
	v_and_b32_e32 v115, 0xffff0000, v224
	v_lshlrev_b32_e32 v108, 16, v225
	v_and_b32_e32 v109, 0xffff0000, v225
	v_pk_add_f32 v[62:63], v[62:63], v[106:107]
	v_pk_add_f32 v[60:61], v[60:61], v[112:113]
	v_pk_add_f32 v[106:107], v[58:59], v[108:109]
	v_pk_add_f32 v[108:109], v[56:57], v[114:115]
	v_cvt_pk_bf16_f32 v56, v60, v61
	v_cvt_pk_bf16_f32 v57, v62, v63
	v_cvt_pk_bf16_f32 v58, v108, v109
	v_cvt_pk_bf16_f32 v59, v106, v107
	global_store_dwordx4 v[110:111], v[56:59], off
	s_nop 1
	v_mul_f32_e32 v56, v61, v61
	v_mul_f32_e32 v57, v63, v63
	v_fmac_f32_e32 v56, v60, v60
	v_fmac_f32_e32 v57, v62, v62
	v_add_f32_e32 v56, v56, v57
	v_mul_f32_e32 v57, v109, v109
	v_mul_f32_e32 v58, v107, v107
	v_fmac_f32_e32 v57, v108, v108
	v_fmac_f32_e32 v58, v106, v106
	v_add_f32_e32 v57, v57, v58
	v_add_f32_e32 v106, v56, v57
	v_lshlrev_b32_e32 v56, 16, v226
	v_and_b32_e32 v57, 0xffff0000, v226
	v_lshlrev_b32_e32 v58, 16, v227
	v_and_b32_e32 v59, 0xffff0000, v227
	v_lshlrev_b32_e32 v60, 16, v228
	v_and_b32_e32 v61, 0xffff0000, v228
	v_lshlrev_b32_e32 v62, 16, v229
	v_and_b32_e32 v63, 0xffff0000, v229
	v_pk_add_f32 v[54:55], v[54:55], v[58:59]
	v_pk_add_f32 v[52:53], v[52:53], v[56:57]
	v_pk_add_f32 v[56:57], v[50:51], v[62:63]
	v_pk_add_f32 v[58:59], v[48:49], v[60:61]
	v_cvt_pk_bf16_f32 v48, v52, v53
	v_cvt_pk_bf16_f32 v49, v54, v55
	v_cvt_pk_bf16_f32 v50, v58, v59
	v_cvt_pk_bf16_f32 v51, v56, v57
	global_store_dwordx4 v[110:111], v[48:51], off offset:256
	s_nop 1
	v_mul_f32_e32 v48, v53, v53
	v_mul_f32_e32 v49, v55, v55
	v_fmac_f32_e32 v48, v52, v52
	v_fmac_f32_e32 v49, v54, v54
	v_add_f32_e32 v48, v48, v49
	v_mul_f32_e32 v49, v59, v59
	v_mul_f32_e32 v50, v57, v57
	v_fmac_f32_e32 v49, v58, v58
	v_fmac_f32_e32 v50, v56, v56
	v_add_f32_e32 v49, v49, v50
	v_add_f32_e32 v48, v48, v49
	v_add_f32_e32 v48, v106, v48
	ds_bpermute_b32 v49, v207, v48
	s_waitcnt lgkmcnt(0)
	v_add_f32_e32 v48, v48, v49
	ds_bpermute_b32 v49, v208, v48
	s_and_saveexec_b64 s[10:11], s[40:41]
	s_cbranch_execz .LBB0_1238
	s_waitcnt lgkmcnt(0)
	v_add_f32_e32 v50, v48, v49
	v_lshlrev_b64 v[48:49], 6, v[104:105]
	v_lshl_add_u64 v[48:49], s[0:1], 0, v[48:49]
	v_lshl_add_u64 v[48:49], s[26:27], 2, v[48:49]
	s_lshl_b32 s64, s39, 2
	v_lshl_add_u64 v[48:49], v[48:49], 0, s[64:65]
	global_store_dword v[48:49], v50, off
.LBB0_1238:
	s_or_b64 exec, exec, s[10:11]
	v_lshlrev_b32_e32 v48, 16, v230
	s_waitcnt lgkmcnt(0)
	v_and_b32_e32 v49, 0xffff0000, v230
	v_lshlrev_b32_e32 v50, 16, v231
	v_and_b32_e32 v51, 0xffff0000, v231
	v_lshlrev_b32_e32 v52, 16, v232
	v_and_b32_e32 v53, 0xffff0000, v232
	v_pk_add_f32 v[44:45], v[44:45], v[48:49]
	v_pk_add_f32 v[46:47], v[46:47], v[50:51]
	v_pk_add_f32 v[50:51], v[40:41], v[52:53]
	v_cvt_pk_bf16_f32 v40, v44, v45
	v_mul_f32_e32 v45, v45, v45
	v_lshlrev_b32_e32 v54, 16, v233
	v_and_b32_e32 v55, 0xffff0000, v233
	v_fmac_f32_e32 v45, v44, v44
	v_mul_f32_e32 v44, v47, v47
	v_pk_add_f32 v[48:49], v[42:43], v[54:55]
	v_fmac_f32_e32 v44, v46, v46
	v_cvt_pk_bf16_f32 v41, v46, v47
	v_add_f32_e32 v44, v45, v44
	v_mul_f32_e32 v45, v51, v51
	v_mul_f32_e32 v46, v49, v49
	v_fmac_f32_e32 v45, v50, v50
	v_fmac_f32_e32 v46, v48, v48
	v_add_f32_e32 v45, v45, v46
	v_add_f32_e32 v52, v44, v45
	v_lshlrev_b32_e32 v44, 16, v234
	v_and_b32_e32 v45, 0xffff0000, v234
	v_lshlrev_b32_e32 v46, 16, v235
	v_and_b32_e32 v47, 0xffff0000, v235
	v_cvt_pk_bf16_f32 v43, v48, v49
	v_lshlrev_b32_e32 v48, 16, v236
	v_and_b32_e32 v49, 0xffff0000, v236
	v_pk_add_f32 v[38:39], v[38:39], v[46:47]
	v_pk_add_f32 v[36:37], v[36:37], v[44:45]
	v_cvt_pk_bf16_f32 v42, v50, v51
	v_lshlrev_b32_e32 v50, 16, v237
	v_and_b32_e32 v51, 0xffff0000, v237
	v_pk_add_f32 v[46:47], v[32:33], v[48:49]
	v_mul_f32_e32 v32, v37, v37
	v_mul_f32_e32 v33, v39, v39
	v_pk_add_f32 v[44:45], v[34:35], v[50:51]
	v_fmac_f32_e32 v32, v36, v36
	v_fmac_f32_e32 v33, v38, v38
	v_add_f32_e32 v32, v32, v33
	v_mul_f32_e32 v33, v47, v47
	v_mul_f32_e32 v34, v45, v45
	v_fmac_f32_e32 v33, v46, v46
	v_fmac_f32_e32 v34, v44, v44
	v_add_f32_e32 v33, v33, v34
	v_add_f32_e32 v32, v32, v33
	v_add_f32_e32 v35, v52, v32
	ds_bpermute_b32 v50, v207, v35
	v_lshl_add_u64 v[32:33], s[16:17], 0, v[102:103]
	v_lshl_add_u64 v[48:49], v[166:167], 1, v[32:33]
	v_cvt_pk_bf16_f32 v34, v36, v37
	v_cvt_pk_bf16_f32 v36, v46, v47
	s_waitcnt lgkmcnt(0)
	v_add_f32_e32 v32, v35, v50
	ds_bpermute_b32 v33, v208, v32
	v_cvt_pk_bf16_f32 v35, v38, v39
	v_cvt_pk_bf16_f32 v37, v44, v45
	global_store_dwordx4 v[48:49], v[40:43], off
	global_store_dwordx4 v[48:49], v[34:37], off offset:256
	s_and_saveexec_b64 s[10:11], s[40:41]
	s_cbranch_execz .LBB0_1240
	s_waitcnt lgkmcnt(0)
	v_add_f32_e32 v34, v32, v33
	v_lshlrev_b64 v[32:33], 6, v[100:101]
	v_lshl_add_u64 v[32:33], s[0:1], 0, v[32:33]
	v_lshl_add_u64 v[32:33], s[26:27], 2, v[32:33]
	s_lshl_b32 s64, s39, 2
	v_lshl_add_u64 v[32:33], v[32:33], 0, s[64:65]
	global_store_dword v[32:33], v34, off
.LBB0_1240:
	s_or_b64 exec, exec, s[10:11]
	v_lshlrev_b32_e32 v32, 16, v238
	s_waitcnt lgkmcnt(0)
	v_and_b32_e32 v33, 0xffff0000, v238
	v_lshlrev_b32_e32 v34, 16, v239
	v_and_b32_e32 v35, 0xffff0000, v239
	v_lshlrev_b32_e32 v36, 16, v240
	v_and_b32_e32 v37, 0xffff0000, v240
	v_pk_add_f32 v[28:29], v[28:29], v[32:33]
	v_pk_add_f32 v[30:31], v[30:31], v[34:35]
	v_pk_add_f32 v[34:35], v[24:25], v[36:37]
	v_cvt_pk_bf16_f32 v24, v28, v29
	v_mul_f32_e32 v29, v29, v29
	v_lshlrev_b32_e32 v38, 16, v241
	v_and_b32_e32 v39, 0xffff0000, v241
	v_fmac_f32_e32 v29, v28, v28
	v_mul_f32_e32 v28, v31, v31
	v_pk_add_f32 v[32:33], v[26:27], v[38:39]
	v_fmac_f32_e32 v28, v30, v30
	v_cvt_pk_bf16_f32 v25, v30, v31
	v_add_f32_e32 v28, v29, v28
	v_mul_f32_e32 v29, v35, v35
	v_mul_f32_e32 v30, v33, v33
	v_fmac_f32_e32 v29, v34, v34
	v_fmac_f32_e32 v30, v32, v32
	v_add_f32_e32 v29, v29, v30
	v_add_f32_e32 v36, v28, v29
	v_lshlrev_b32_e32 v28, 16, v242
	v_and_b32_e32 v29, 0xffff0000, v242
	v_lshlrev_b32_e32 v30, 16, v243
	v_and_b32_e32 v31, 0xffff0000, v243
	v_cvt_pk_bf16_f32 v27, v32, v33
	v_lshlrev_b32_e32 v32, 16, v244
	v_and_b32_e32 v33, 0xffff0000, v244
	v_pk_add_f32 v[22:23], v[22:23], v[30:31]
	v_pk_add_f32 v[20:21], v[20:21], v[28:29]
	v_cvt_pk_bf16_f32 v26, v34, v35
	v_lshlrev_b32_e32 v34, 16, v245
	v_and_b32_e32 v35, 0xffff0000, v245
	v_pk_add_f32 v[30:31], v[16:17], v[32:33]
	v_mul_f32_e32 v16, v21, v21
	v_mul_f32_e32 v17, v23, v23
	v_pk_add_f32 v[28:29], v[18:19], v[34:35]
	v_fmac_f32_e32 v16, v20, v20
	v_fmac_f32_e32 v17, v22, v22
	v_add_f32_e32 v16, v16, v17
	v_mul_f32_e32 v17, v31, v31
	v_mul_f32_e32 v18, v29, v29
	v_fmac_f32_e32 v17, v30, v30
	v_fmac_f32_e32 v18, v28, v28
	v_add_f32_e32 v17, v17, v18
	v_add_f32_e32 v16, v16, v17
	v_add_f32_e32 v19, v36, v16
	ds_bpermute_b32 v34, v207, v19
	v_lshl_add_u64 v[16:17], s[16:17], 0, v[98:99]
	v_lshl_add_u64 v[32:33], v[166:167], 1, v[16:17]
	v_cvt_pk_bf16_f32 v18, v20, v21
	v_cvt_pk_bf16_f32 v20, v30, v31
	s_waitcnt lgkmcnt(0)
	v_add_f32_e32 v16, v19, v34
	ds_bpermute_b32 v17, v208, v16
	v_cvt_pk_bf16_f32 v19, v22, v23
	v_cvt_pk_bf16_f32 v21, v28, v29
	global_store_dwordx4 v[32:33], v[24:27], off
	global_store_dwordx4 v[32:33], v[18:21], off offset:256
	s_and_saveexec_b64 s[10:11], s[40:41]
	s_cbranch_execz .LBB0_1242
	s_waitcnt lgkmcnt(0)
	v_add_f32_e32 v18, v16, v17
	v_lshlrev_b64 v[16:17], 6, v[96:97]
	v_lshl_add_u64 v[16:17], s[0:1], 0, v[16:17]
	v_lshl_add_u64 v[16:17], s[26:27], 2, v[16:17]
	s_lshl_b32 s64, s39, 2
	v_lshl_add_u64 v[16:17], v[16:17], 0, s[64:65]
	global_store_dword v[16:17], v18, off
.LBB0_1242:
	s_or_b64 exec, exec, s[10:11]
	v_lshlrev_b32_e32 v16, 16, v246
	s_waitcnt lgkmcnt(0)
	v_and_b32_e32 v17, 0xffff0000, v246
	v_lshlrev_b32_e32 v18, 16, v247
	v_and_b32_e32 v19, 0xffff0000, v247
	v_lshlrev_b32_e32 v20, 16, v248
	v_and_b32_e32 v21, 0xffff0000, v248
	v_pk_add_f32 v[12:13], v[12:13], v[16:17]
	v_pk_add_f32 v[14:15], v[14:15], v[18:19]
	v_pk_add_f32 v[18:19], v[8:9], v[20:21]
	v_cvt_pk_bf16_f32 v8, v12, v13
	v_mul_f32_e32 v13, v13, v13
	v_lshlrev_b32_e32 v22, 16, v249
	v_and_b32_e32 v23, 0xffff0000, v249
	v_fmac_f32_e32 v13, v12, v12
	v_mul_f32_e32 v12, v15, v15
	v_pk_add_f32 v[16:17], v[10:11], v[22:23]
	v_fmac_f32_e32 v12, v14, v14
	v_cvt_pk_bf16_f32 v9, v14, v15
	v_add_f32_e32 v12, v13, v12
	v_mul_f32_e32 v13, v19, v19
	v_mul_f32_e32 v14, v17, v17
	v_fmac_f32_e32 v13, v18, v18
	v_fmac_f32_e32 v14, v16, v16
	v_add_f32_e32 v13, v13, v14
	v_add_f32_e32 v20, v12, v13
	s_waitcnt vmcnt(8)
	v_lshlrev_b32_e32 v12, 16, v64
	v_and_b32_e32 v13, 0xffff0000, v64
	v_lshlrev_b32_e32 v14, 16, v65
	v_and_b32_e32 v15, 0xffff0000, v65
	v_cvt_pk_bf16_f32 v11, v16, v17
	v_lshlrev_b32_e32 v16, 16, v66
	v_and_b32_e32 v17, 0xffff0000, v66
	v_pk_add_f32 v[6:7], v[6:7], v[14:15]
	v_pk_add_f32 v[4:5], v[4:5], v[12:13]
	v_cvt_pk_bf16_f32 v10, v18, v19
	v_lshlrev_b32_e32 v18, 16, v67
	v_and_b32_e32 v19, 0xffff0000, v67
	v_pk_add_f32 v[14:15], v[0:1], v[16:17]
	v_mul_f32_e32 v0, v5, v5
	v_mul_f32_e32 v1, v7, v7
	v_pk_add_f32 v[12:13], v[2:3], v[18:19]
	v_fmac_f32_e32 v0, v4, v4
	v_fmac_f32_e32 v1, v6, v6
	v_add_f32_e32 v0, v0, v1
	v_mul_f32_e32 v1, v15, v15
	v_mul_f32_e32 v2, v13, v13
	v_fmac_f32_e32 v1, v14, v14
	v_fmac_f32_e32 v2, v12, v12
	v_add_f32_e32 v1, v1, v2
	v_add_f32_e32 v0, v0, v1
	v_add_f32_e32 v3, v20, v0
	ds_bpermute_b32 v18, v207, v3
	v_lshl_add_u64 v[0:1], s[16:17], 0, v[94:95]
	v_lshl_add_u64 v[16:17], v[166:167], 1, v[0:1]
	v_cvt_pk_bf16_f32 v2, v4, v5
	v_cvt_pk_bf16_f32 v4, v14, v15
	s_waitcnt lgkmcnt(0)
	v_add_f32_e32 v0, v3, v18
	ds_bpermute_b32 v1, v208, v0
	v_cvt_pk_bf16_f32 v3, v6, v7
	v_cvt_pk_bf16_f32 v5, v12, v13
	global_store_dwordx4 v[16:17], v[8:11], off
	global_store_dwordx4 v[16:17], v[2:5], off offset:256
	s_and_saveexec_b64 s[10:11], s[40:41]
	s_cbranch_execz .LBB0_1244
	s_waitcnt lgkmcnt(0)
	v_add_f32_e32 v2, v0, v1
	v_lshlrev_b64 v[0:1], 6, v[92:93]
	v_lshl_add_u64 v[0:1], s[0:1], 0, v[0:1]
	v_lshl_add_u64 v[0:1], s[26:27], 2, v[0:1]
	s_lshl_b32 s64, s39, 2
	v_lshl_add_u64 v[0:1], v[0:1], 0, s[64:65]
	global_store_dword v[0:1], v2, off
